# GEMM K-loops: per-segment s_setprio raise/lower pairs removed (strategy 4: no dynamic priority toggling)
# speedup vs baseline: 1.0032x; 1.0032x over previous
.LBB0_304:
	s_add_u32 s14, s12, 0x4000
	s_addc_u32 s15, s13, 0
	s_cmp_eq_u32 s50, 28
	s_cselect_b32 s22, s46, s14
	s_cselect_b32 s23, s47, s15
	s_cselect_b32 s16, s48, s41
	s_cselect_b32 s17, s49, s43
	s_add_u32 s14, s22, 0x8000
	s_addc_u32 s15, s23, 0
	s_add_i32 s51, 0, 0x10000
	s_add_i32 s54, 0, 0x14000
	ds_read_b128 v[38:41], v229
	ds_read_b128 v[42:45], v229 offset:1024
	ds_read_b128 v[50:53], v229 offset:2048
	ds_read_b128 v[54:57], v229 offset:3072
	ds_read_b128 v[146:149], v229 offset:16384
	ds_read_b128 v[150:153], v229 offset:17408
	ds_read_b128 v[166:169], v229 offset:18432
	ds_read_b128 v[170:173], v229 offset:19456
	s_add_i32 m0, s59, 0xc000
	ds_read_b128 v[174:177], v206
	ds_read_b128 v[178:181], v206 offset:1024
	ds_read_b128 v[182:185], v206 offset:2048
	ds_read_b128 v[186:189], v206 offset:3072
	ds_read_b128 v[190:193], v206 offset:4096
	ds_read_b128 v[194:197], v206 offset:5120
	ds_read_b128 v[198:201], v206 offset:6144
	ds_read_b128 v[212:215], v206 offset:7168
	global_load_lds_dwordx4 v154, s[12:13]
	s_add_i32 m0, s59, 0xe000
	s_nop 0
	global_load_lds_dwordx4 v156, s[12:13]
	s_waitcnt vmcnt(8) lgkmcnt(0)
	s_barrier
	v_mfma_f32_16x16x32_bf16 v[142:145], v[38:41], v[174:177], v[142:145]
	v_mfma_f32_16x16x32_bf16 v[138:141], v[50:53], v[174:177], v[138:141]
	v_mfma_f32_16x16x32_bf16 v[126:129], v[38:41], v[182:185], v[126:129]
	v_mfma_f32_16x16x32_bf16 v[122:125], v[50:53], v[182:185], v[122:125]
	v_mfma_f32_16x16x32_bf16 v[110:113], v[38:41], v[190:193], v[110:113]
	v_mfma_f32_16x16x32_bf16 v[106:109], v[50:53], v[190:193], v[106:109]
	v_mfma_f32_16x16x32_bf16 v[94:97], v[38:41], v[198:201], v[94:97]
	v_mfma_f32_16x16x32_bf16 v[90:93], v[50:53], v[198:201], v[90:93]
	v_mfma_f32_16x16x32_bf16 v[142:145], v[42:45], v[178:181], v[142:145]
	v_mfma_f32_16x16x32_bf16 v[138:141], v[54:57], v[178:181], v[138:141]
	v_mfma_f32_16x16x32_bf16 v[126:129], v[42:45], v[186:189], v[126:129]
	v_mfma_f32_16x16x32_bf16 v[122:125], v[54:57], v[186:189], v[122:125]
	v_mfma_f32_16x16x32_bf16 v[110:113], v[42:45], v[194:197], v[110:113]
	v_mfma_f32_16x16x32_bf16 v[106:109], v[54:57], v[194:197], v[106:109]
	v_mfma_f32_16x16x32_bf16 v[94:97], v[42:45], v[212:215], v[94:97]
	v_mfma_f32_16x16x32_bf16 v[90:93], v[54:57], v[212:215], v[90:93]
	v_mfma_f32_16x16x32_bf16 v[134:137], v[146:149], v[174:177], v[134:137]
	v_mfma_f32_16x16x32_bf16 v[130:133], v[166:169], v[174:177], v[130:133]
	v_mfma_f32_16x16x32_bf16 v[118:121], v[146:149], v[182:185], v[118:121]
	v_mfma_f32_16x16x32_bf16 v[114:117], v[166:169], v[182:185], v[114:117]
	v_mfma_f32_16x16x32_bf16 v[102:105], v[146:149], v[190:193], v[102:105]
	v_mfma_f32_16x16x32_bf16 v[98:101], v[166:169], v[190:193], v[98:101]
	v_mfma_f32_16x16x32_bf16 v[86:89], v[146:149], v[198:201], v[86:89]
	v_mfma_f32_16x16x32_bf16 v[82:85], v[166:169], v[198:201], v[82:85]
	v_mfma_f32_16x16x32_bf16 v[134:137], v[150:153], v[178:181], v[134:137]
	v_mfma_f32_16x16x32_bf16 v[130:133], v[170:173], v[178:181], v[130:133]
	v_mfma_f32_16x16x32_bf16 v[118:121], v[150:153], v[186:189], v[118:121]
	v_mfma_f32_16x16x32_bf16 v[114:117], v[170:173], v[186:189], v[114:117]
	v_mfma_f32_16x16x32_bf16 v[102:105], v[150:153], v[194:197], v[102:105]
	v_mfma_f32_16x16x32_bf16 v[98:101], v[170:173], v[194:197], v[98:101]
	v_mfma_f32_16x16x32_bf16 v[86:89], v[150:153], v[212:215], v[86:89]
	v_mfma_f32_16x16x32_bf16 v[82:85], v[170:173], v[212:215], v[82:85]
	s_barrier
	s_add_i32 s51, s51, s58
	s_mov_b32 m0, s51
	ds_read_b128 v[174:177], v206 offset:16384
	ds_read_b128 v[178:181], v206 offset:17408
	ds_read_b128 v[182:185], v206 offset:18432
	ds_read_b128 v[186:189], v206 offset:19456
	ds_read_b128 v[190:193], v206 offset:20480
	ds_read_b128 v[194:197], v206 offset:21504
	ds_read_b128 v[198:201], v206 offset:22528
	ds_read_b128 v[212:215], v206 offset:23552
	global_load_lds_dwordx4 v154, s[16:17]
	s_add_i32 m0, s51, 0x2000
	s_add_u32 s52, s16, 0x4000
	s_addc_u32 s53, s17, 0
	s_add_i32 s51, s54, s58
	global_load_lds_dwordx4 v156, s[16:17]
	s_mov_b32 m0, s51
	s_nop 0
	global_load_lds_dwordx4 v154, s[52:53]
	s_add_i32 m0, s51, 0x2000
	s_nop 0
	global_load_lds_dwordx4 v156, s[52:53]
	s_mov_b32 m0, s59
	s_nop 0
	global_load_lds_dwordx4 v154, s[22:23]
	s_mov_b32 m0, s60
	s_nop 0
	global_load_lds_dwordx4 v156, s[22:23]
	s_waitcnt vmcnt(8) lgkmcnt(0)
	s_barrier
	v_mfma_f32_16x16x32_bf16 v[78:81], v[38:41], v[174:177], v[78:81]
	v_mfma_f32_16x16x32_bf16 v[74:77], v[50:53], v[174:177], v[74:77]
	v_mfma_f32_16x16x32_bf16 v[62:65], v[38:41], v[182:185], v[62:65]
	v_mfma_f32_16x16x32_bf16 v[58:61], v[50:53], v[182:185], v[58:61]
	v_mfma_f32_16x16x32_bf16 v[30:33], v[38:41], v[190:193], v[30:33]
	v_mfma_f32_16x16x32_bf16 v[26:29], v[50:53], v[190:193], v[26:29]
	v_mfma_f32_16x16x32_bf16 v[14:17], v[38:41], v[198:201], v[14:17]
	v_mfma_f32_16x16x32_bf16 v[10:13], v[50:53], v[198:201], v[10:13]
	v_mfma_f32_16x16x32_bf16 v[78:81], v[42:45], v[178:181], v[78:81]
	v_mfma_f32_16x16x32_bf16 v[74:77], v[54:57], v[178:181], v[74:77]
	v_mfma_f32_16x16x32_bf16 v[62:65], v[42:45], v[186:189], v[62:65]
	v_mfma_f32_16x16x32_bf16 v[58:61], v[54:57], v[186:189], v[58:61]
	v_mfma_f32_16x16x32_bf16 v[30:33], v[42:45], v[194:197], v[30:33]
	v_mfma_f32_16x16x32_bf16 v[26:29], v[54:57], v[194:197], v[26:29]
	v_mfma_f32_16x16x32_bf16 v[14:17], v[42:45], v[212:215], v[14:17]
	v_mfma_f32_16x16x32_bf16 v[10:13], v[54:57], v[212:215], v[10:13]
	v_mfma_f32_16x16x32_bf16 v[46:49], v[146:149], v[182:185], v[46:49]
	v_mfma_f32_16x16x32_bf16 v[34:37], v[166:169], v[182:185], v[34:37]
	v_mfma_f32_16x16x32_bf16 v[22:25], v[146:149], v[190:193], v[22:25]
	v_mfma_f32_16x16x32_bf16 v[18:21], v[166:169], v[190:193], v[18:21]
	v_mfma_f32_16x16x32_bf16 v[6:9], v[146:149], v[198:201], v[6:9]
	v_mfma_f32_16x16x32_bf16 v[2:5], v[166:169], v[198:201], v[2:5]
	v_mfma_f32_16x16x32_bf16 v[38:41], v[146:149], v[174:177], v[70:73]
	v_mfma_f32_16x16x32_bf16 v[42:45], v[166:169], v[174:177], v[66:69]
	v_mfma_f32_16x16x32_bf16 v[46:49], v[150:153], v[186:189], v[46:49]
	v_mfma_f32_16x16x32_bf16 v[34:37], v[170:173], v[186:189], v[34:37]
	v_mfma_f32_16x16x32_bf16 v[22:25], v[150:153], v[194:197], v[22:25]
	v_mfma_f32_16x16x32_bf16 v[18:21], v[170:173], v[194:197], v[18:21]
	v_mfma_f32_16x16x32_bf16 v[6:9], v[150:153], v[212:215], v[6:9]
	v_mfma_f32_16x16x32_bf16 v[2:5], v[170:173], v[212:215], v[2:5]
	v_mfma_f32_16x16x32_bf16 v[38:41], v[150:153], v[178:181], v[38:41]
	v_mfma_f32_16x16x32_bf16 v[42:45], v[170:173], v[178:181], v[42:45]
	s_barrier
	s_add_i32 s51, 0, 0x18000
	s_add_i32 s52, 0, 0x1c000
	ds_read_b128 v[50:53], v229 offset:32768
	ds_read_b128 v[54:57], v229 offset:33792
	ds_read_b128 v[66:69], v229 offset:34816
	ds_read_b128 v[70:73], v229 offset:35840
	ds_read_b128 v[146:149], v229 offset:49152
	ds_read_b128 v[150:153], v229 offset:50176
	ds_read_b128 v[166:169], v229 offset:51200
	ds_read_b128 v[170:173], v229 offset:52224
	s_add_u32 s22, s22, 0x4000
	s_addc_u32 s23, s23, 0
	s_mov_b32 m0, s61
	ds_read_b128 v[174:177], v206 offset:32768
	ds_read_b128 v[178:181], v206 offset:33792
	ds_read_b128 v[182:185], v206 offset:34816
	ds_read_b128 v[186:189], v206 offset:35840
	ds_read_b128 v[190:193], v206 offset:36864
	ds_read_b128 v[194:197], v206 offset:37888
	ds_read_b128 v[198:201], v206 offset:38912
	ds_read_b128 v[212:215], v206 offset:39936
	global_load_lds_dwordx4 v154, s[22:23]
	s_mov_b32 m0, s62
	s_nop 0
	global_load_lds_dwordx4 v156, s[22:23]
	s_waitcnt vmcnt(8) lgkmcnt(0)
	s_barrier
	v_mfma_f32_16x16x32_bf16 v[142:145], v[50:53], v[174:177], v[142:145]
	v_mfma_f32_16x16x32_bf16 v[138:141], v[66:69], v[174:177], v[138:141]
	v_mfma_f32_16x16x32_bf16 v[126:129], v[50:53], v[182:185], v[126:129]
	v_mfma_f32_16x16x32_bf16 v[122:125], v[66:69], v[182:185], v[122:125]
	v_mfma_f32_16x16x32_bf16 v[110:113], v[50:53], v[190:193], v[110:113]
	v_mfma_f32_16x16x32_bf16 v[106:109], v[66:69], v[190:193], v[106:109]
	v_mfma_f32_16x16x32_bf16 v[94:97], v[50:53], v[198:201], v[94:97]
	v_mfma_f32_16x16x32_bf16 v[90:93], v[66:69], v[198:201], v[90:93]
	v_mfma_f32_16x16x32_bf16 v[142:145], v[54:57], v[178:181], v[142:145]
	v_mfma_f32_16x16x32_bf16 v[138:141], v[70:73], v[178:181], v[138:141]
	v_mfma_f32_16x16x32_bf16 v[126:129], v[54:57], v[186:189], v[126:129]
	v_mfma_f32_16x16x32_bf16 v[122:125], v[70:73], v[186:189], v[122:125]
	v_mfma_f32_16x16x32_bf16 v[110:113], v[54:57], v[194:197], v[110:113]
	v_mfma_f32_16x16x32_bf16 v[106:109], v[70:73], v[194:197], v[106:109]
	v_mfma_f32_16x16x32_bf16 v[94:97], v[54:57], v[212:215], v[94:97]
	v_mfma_f32_16x16x32_bf16 v[90:93], v[70:73], v[212:215], v[90:93]
	v_mfma_f32_16x16x32_bf16 v[134:137], v[146:149], v[174:177], v[134:137]
	v_mfma_f32_16x16x32_bf16 v[130:133], v[166:169], v[174:177], v[130:133]
	v_mfma_f32_16x16x32_bf16 v[118:121], v[146:149], v[182:185], v[118:121]
	v_mfma_f32_16x16x32_bf16 v[114:117], v[166:169], v[182:185], v[114:117]
	v_mfma_f32_16x16x32_bf16 v[102:105], v[146:149], v[190:193], v[102:105]
	v_mfma_f32_16x16x32_bf16 v[98:101], v[166:169], v[190:193], v[98:101]
	v_mfma_f32_16x16x32_bf16 v[86:89], v[146:149], v[198:201], v[86:89]
	v_mfma_f32_16x16x32_bf16 v[82:85], v[166:169], v[198:201], v[82:85]
	v_mfma_f32_16x16x32_bf16 v[134:137], v[150:153], v[178:181], v[134:137]
	v_mfma_f32_16x16x32_bf16 v[130:133], v[170:173], v[178:181], v[130:133]
	v_mfma_f32_16x16x32_bf16 v[118:121], v[150:153], v[186:189], v[118:121]
	v_mfma_f32_16x16x32_bf16 v[114:117], v[170:173], v[186:189], v[114:117]
	v_mfma_f32_16x16x32_bf16 v[102:105], v[150:153], v[194:197], v[102:105]
	v_mfma_f32_16x16x32_bf16 v[98:101], v[170:173], v[194:197], v[98:101]
	v_mfma_f32_16x16x32_bf16 v[86:89], v[150:153], v[212:215], v[86:89]
	v_mfma_f32_16x16x32_bf16 v[82:85], v[170:173], v[212:215], v[82:85]
	s_barrier
	s_add_u32 s22, s16, 0x8000
	s_addc_u32 s23, s17, 0
	s_add_i32 s51, s51, s58
	s_mov_b32 m0, s51
	ds_read_b128 v[174:177], v206 offset:49152
	ds_read_b128 v[178:181], v206 offset:50176
	ds_read_b128 v[182:185], v206 offset:51200
	ds_read_b128 v[186:189], v206 offset:52224
	ds_read_b128 v[190:193], v206 offset:53248
	ds_read_b128 v[194:197], v206 offset:54272
	ds_read_b128 v[198:201], v206 offset:55296
	ds_read_b128 v[212:215], v206 offset:56320
	global_load_lds_dwordx4 v154, s[22:23]
	s_add_i32 m0, s51, 0x2000
	s_add_u32 s16, s16, 0xc000
	s_addc_u32 s17, s17, 0
	global_load_lds_dwordx4 v156, s[22:23]
	s_add_i32 s22, s52, s58
	s_mov_b32 m0, s22
	s_nop 0
	global_load_lds_dwordx4 v154, s[16:17]
	s_add_i32 m0, s22, 0x2000
	s_nop 0
	global_load_lds_dwordx4 v156, s[16:17]
	s_mov_b32 m0, s72
	s_nop 0
	global_load_lds_dwordx4 v154, s[14:15]
	s_mov_b32 m0, s73
	s_nop 0
	global_load_lds_dwordx4 v156, s[14:15]
	s_waitcnt vmcnt(8) lgkmcnt(0)
	s_barrier
	v_mfma_f32_16x16x32_bf16 v[78:81], v[50:53], v[174:177], v[78:81]
	v_mfma_f32_16x16x32_bf16 v[74:77], v[66:69], v[174:177], v[74:77]
	v_mfma_f32_16x16x32_bf16 v[62:65], v[50:53], v[182:185], v[62:65]
	v_mfma_f32_16x16x32_bf16 v[58:61], v[66:69], v[182:185], v[58:61]
	v_mfma_f32_16x16x32_bf16 v[30:33], v[50:53], v[190:193], v[30:33]
	v_mfma_f32_16x16x32_bf16 v[26:29], v[66:69], v[190:193], v[26:29]
	v_mfma_f32_16x16x32_bf16 v[14:17], v[50:53], v[198:201], v[14:17]
	v_mfma_f32_16x16x32_bf16 v[10:13], v[66:69], v[198:201], v[10:13]
	v_mfma_f32_16x16x32_bf16 v[78:81], v[54:57], v[178:181], v[78:81]
	v_mfma_f32_16x16x32_bf16 v[74:77], v[70:73], v[178:181], v[74:77]
	v_mfma_f32_16x16x32_bf16 v[62:65], v[54:57], v[186:189], v[62:65]
	v_mfma_f32_16x16x32_bf16 v[58:61], v[70:73], v[186:189], v[58:61]
	v_mfma_f32_16x16x32_bf16 v[30:33], v[54:57], v[194:197], v[30:33]
	v_mfma_f32_16x16x32_bf16 v[26:29], v[70:73], v[194:197], v[26:29]
	v_mfma_f32_16x16x32_bf16 v[14:17], v[54:57], v[212:215], v[14:17]
	v_mfma_f32_16x16x32_bf16 v[10:13], v[70:73], v[212:215], v[10:13]
	v_mfma_f32_16x16x32_bf16 v[38:41], v[146:149], v[174:177], v[38:41]
	v_mfma_f32_16x16x32_bf16 v[70:73], v[150:153], v[178:181], v[38:41]
	v_mfma_f32_16x16x32_bf16 v[38:41], v[166:169], v[174:177], v[42:45]
	v_mfma_f32_16x16x32_bf16 v[66:69], v[170:173], v[178:181], v[38:41]
	v_mfma_f32_16x16x32_bf16 v[38:41], v[146:149], v[182:185], v[46:49]
	v_mfma_f32_16x16x32_bf16 v[34:37], v[166:169], v[182:185], v[34:37]
	v_mfma_f32_16x16x32_bf16 v[22:25], v[146:149], v[190:193], v[22:25]
	v_mfma_f32_16x16x32_bf16 v[18:21], v[166:169], v[190:193], v[18:21]
	v_mfma_f32_16x16x32_bf16 v[6:9], v[146:149], v[198:201], v[6:9]
	v_mfma_f32_16x16x32_bf16 v[2:5], v[166:169], v[198:201], v[2:5]
	v_mfma_f32_16x16x32_bf16 v[46:49], v[150:153], v[186:189], v[38:41]
	v_mfma_f32_16x16x32_bf16 v[34:37], v[170:173], v[186:189], v[34:37]
	v_mfma_f32_16x16x32_bf16 v[22:25], v[150:153], v[194:197], v[22:25]
	v_mfma_f32_16x16x32_bf16 v[18:21], v[170:173], v[194:197], v[18:21]
	v_mfma_f32_16x16x32_bf16 v[6:9], v[150:153], v[212:215], v[6:9]
	v_mfma_f32_16x16x32_bf16 v[2:5], v[170:173], v[212:215], v[2:5]
	s_barrier
	s_add_i32 s50, s50, 2
	s_add_u32 s41, s41, 0x10000
	s_addc_u32 s43, s43, 0
	s_add_u32 s12, s12, 0x10000
	s_addc_u32 s13, s13, 0
	s_cmp_gt_u32 s50, 29
	s_cbranch_scc0 .LBB0_304
	s_and_b64 vcc, exec, s[26:27]
	s_cbranch_vccz .LBB0_307
	s_barrier

.LBB0_1111:
	s_add_u32 s14, s12, 0x4000
	s_addc_u32 s15, s13, 0
	s_cmp_eq_u32 s66, 28
	s_cselect_b32 s22, s42, s14
	s_cselect_b32 s23, s43, s15
	s_cselect_b32 s16, s44, s31
	s_cselect_b32 s17, s45, s41
	s_add_u32 s14, s22, 0x8000
	s_addc_u32 s15, s23, 0
	s_add_i32 s67, 0, 0x10000
	s_add_i32 s70, 0, 0x14000
	ds_read_b128 v[42:45], v229
	ds_read_b128 v[46:49], v229 offset:1024
	ds_read_b128 v[50:53], v229 offset:2048
	ds_read_b128 v[54:57], v229 offset:3072
	ds_read_b128 v[66:69], v229 offset:16384
	ds_read_b128 v[70:73], v229 offset:17408
	ds_read_b128 v[74:77], v229 offset:18432
	ds_read_b128 v[78:81], v229 offset:19456
	s_add_i32 m0, s50, 0xc000
	ds_read_b128 v[162:165], v205
	ds_read_b128 v[166:169], v205 offset:1024
	ds_read_b128 v[170:173], v205 offset:2048
	ds_read_b128 v[174:177], v205 offset:3072
	ds_read_b128 v[178:181], v205 offset:4096
	ds_read_b128 v[182:185], v205 offset:5120
	ds_read_b128 v[192:195], v205 offset:6144
	ds_read_b128 v[196:199], v205 offset:7168
	global_load_lds_dwordx4 v186, s[12:13]
	s_add_i32 m0, s50, 0xe000
	s_nop 0
	global_load_lds_dwordx4 v188, s[12:13]
	s_waitcnt vmcnt(8) lgkmcnt(0)
	s_barrier
	v_mfma_f32_16x16x32_bf16 v[158:161], v[42:45], v[162:165], v[158:161]
	v_mfma_f32_16x16x32_bf16 v[154:157], v[50:53], v[162:165], v[154:157]
	v_mfma_f32_16x16x32_bf16 v[142:145], v[42:45], v[170:173], v[142:145]
	v_mfma_f32_16x16x32_bf16 v[138:141], v[50:53], v[170:173], v[138:141]
	v_mfma_f32_16x16x32_bf16 v[126:129], v[42:45], v[178:181], v[126:129]
	v_mfma_f32_16x16x32_bf16 v[122:125], v[50:53], v[178:181], v[122:125]
	v_mfma_f32_16x16x32_bf16 v[110:113], v[42:45], v[192:195], v[110:113]
	v_mfma_f32_16x16x32_bf16 v[106:109], v[50:53], v[192:195], v[106:109]
	v_mfma_f32_16x16x32_bf16 v[158:161], v[46:49], v[166:169], v[158:161]
	v_mfma_f32_16x16x32_bf16 v[154:157], v[54:57], v[166:169], v[154:157]
	v_mfma_f32_16x16x32_bf16 v[142:145], v[46:49], v[174:177], v[142:145]
	v_mfma_f32_16x16x32_bf16 v[138:141], v[54:57], v[174:177], v[138:141]
	v_mfma_f32_16x16x32_bf16 v[126:129], v[46:49], v[182:185], v[126:129]
	v_mfma_f32_16x16x32_bf16 v[122:125], v[54:57], v[182:185], v[122:125]
	v_mfma_f32_16x16x32_bf16 v[110:113], v[46:49], v[196:199], v[110:113]
	v_mfma_f32_16x16x32_bf16 v[106:109], v[54:57], v[196:199], v[106:109]
	v_mfma_f32_16x16x32_bf16 v[150:153], v[66:69], v[162:165], v[150:153]
	v_mfma_f32_16x16x32_bf16 v[146:149], v[74:77], v[162:165], v[146:149]
	v_mfma_f32_16x16x32_bf16 v[134:137], v[66:69], v[170:173], v[134:137]
	v_mfma_f32_16x16x32_bf16 v[130:133], v[74:77], v[170:173], v[130:133]
	v_mfma_f32_16x16x32_bf16 v[118:121], v[66:69], v[178:181], v[118:121]
	v_mfma_f32_16x16x32_bf16 v[114:117], v[74:77], v[178:181], v[114:117]
	v_mfma_f32_16x16x32_bf16 v[102:105], v[66:69], v[192:195], v[102:105]
	v_mfma_f32_16x16x32_bf16 v[98:101], v[74:77], v[192:195], v[98:101]
	v_mfma_f32_16x16x32_bf16 v[150:153], v[70:73], v[166:169], v[150:153]
	v_mfma_f32_16x16x32_bf16 v[146:149], v[78:81], v[166:169], v[146:149]
	v_mfma_f32_16x16x32_bf16 v[134:137], v[70:73], v[174:177], v[134:137]
	v_mfma_f32_16x16x32_bf16 v[130:133], v[78:81], v[174:177], v[130:133]
	v_mfma_f32_16x16x32_bf16 v[118:121], v[70:73], v[182:185], v[118:121]
	v_mfma_f32_16x16x32_bf16 v[114:117], v[78:81], v[182:185], v[114:117]
	v_mfma_f32_16x16x32_bf16 v[102:105], v[70:73], v[196:199], v[102:105]
	v_mfma_f32_16x16x32_bf16 v[98:101], v[78:81], v[196:199], v[98:101]
	s_barrier
	s_add_i32 s67, s67, s49
	s_mov_b32 m0, s67
	ds_read_b128 v[162:165], v205 offset:16384
	ds_read_b128 v[166:169], v205 offset:17408
	ds_read_b128 v[170:173], v205 offset:18432
	ds_read_b128 v[174:177], v205 offset:19456
	ds_read_b128 v[178:181], v205 offset:20480
	ds_read_b128 v[182:185], v205 offset:21504
	ds_read_b128 v[192:195], v205 offset:22528
	ds_read_b128 v[196:199], v205 offset:23552
	global_load_lds_dwordx4 v186, s[16:17]
	s_add_i32 m0, s67, 0x2000
	s_add_u32 s68, s16, 0x4000
	s_addc_u32 s69, s17, 0
	s_add_i32 s67, s70, s49
	global_load_lds_dwordx4 v188, s[16:17]
	s_mov_b32 m0, s67
	s_nop 0
	global_load_lds_dwordx4 v186, s[68:69]
	s_add_i32 m0, s67, 0x2000
	s_nop 0
	global_load_lds_dwordx4 v188, s[68:69]
	s_mov_b32 m0, s50
	s_nop 0
	global_load_lds_dwordx4 v186, s[22:23]
	s_mov_b32 m0, s51
	s_nop 0
	global_load_lds_dwordx4 v188, s[22:23]
	s_waitcnt vmcnt(8) lgkmcnt(0)
	s_barrier
	v_mfma_f32_16x16x32_bf16 v[94:97], v[42:45], v[162:165], v[94:97]
	v_mfma_f32_16x16x32_bf16 v[90:93], v[50:53], v[162:165], v[90:93]
	v_mfma_f32_16x16x32_bf16 v[62:65], v[42:45], v[170:173], v[62:65]
	v_mfma_f32_16x16x32_bf16 v[58:61], v[50:53], v[170:173], v[58:61]
	v_mfma_f32_16x16x32_bf16 v[30:33], v[42:45], v[178:181], v[30:33]
	v_mfma_f32_16x16x32_bf16 v[26:29], v[50:53], v[178:181], v[26:29]
	v_mfma_f32_16x16x32_bf16 v[14:17], v[42:45], v[192:195], v[14:17]
	v_mfma_f32_16x16x32_bf16 v[10:13], v[50:53], v[192:195], v[10:13]
	v_mfma_f32_16x16x32_bf16 v[94:97], v[46:49], v[166:169], v[94:97]
	v_mfma_f32_16x16x32_bf16 v[90:93], v[54:57], v[166:169], v[90:93]
	v_mfma_f32_16x16x32_bf16 v[62:65], v[46:49], v[174:177], v[62:65]
	v_mfma_f32_16x16x32_bf16 v[58:61], v[54:57], v[174:177], v[58:61]
	v_mfma_f32_16x16x32_bf16 v[30:33], v[46:49], v[182:185], v[30:33]
	v_mfma_f32_16x16x32_bf16 v[26:29], v[54:57], v[182:185], v[26:29]
	v_mfma_f32_16x16x32_bf16 v[14:17], v[46:49], v[196:199], v[14:17]
	v_mfma_f32_16x16x32_bf16 v[10:13], v[54:57], v[196:199], v[10:13]
	v_mfma_f32_16x16x32_bf16 v[38:41], v[66:69], v[170:173], v[38:41]
	v_mfma_f32_16x16x32_bf16 v[34:37], v[74:77], v[170:173], v[34:37]
	v_mfma_f32_16x16x32_bf16 v[22:25], v[66:69], v[178:181], v[22:25]
	v_mfma_f32_16x16x32_bf16 v[18:21], v[74:77], v[178:181], v[18:21]
	v_mfma_f32_16x16x32_bf16 v[6:9], v[66:69], v[192:195], v[6:9]
	v_mfma_f32_16x16x32_bf16 v[2:5], v[74:77], v[192:195], v[2:5]
	v_mfma_f32_16x16x32_bf16 v[42:45], v[66:69], v[162:165], v[86:89]
	v_mfma_f32_16x16x32_bf16 v[46:49], v[74:77], v[162:165], v[82:85]
	v_mfma_f32_16x16x32_bf16 v[38:41], v[70:73], v[174:177], v[38:41]
	v_mfma_f32_16x16x32_bf16 v[34:37], v[78:81], v[174:177], v[34:37]
	v_mfma_f32_16x16x32_bf16 v[22:25], v[70:73], v[182:185], v[22:25]
	v_mfma_f32_16x16x32_bf16 v[18:21], v[78:81], v[182:185], v[18:21]
	v_mfma_f32_16x16x32_bf16 v[6:9], v[70:73], v[196:199], v[6:9]
	v_mfma_f32_16x16x32_bf16 v[2:5], v[78:81], v[196:199], v[2:5]
	v_mfma_f32_16x16x32_bf16 v[42:45], v[70:73], v[166:169], v[42:45]
	v_mfma_f32_16x16x32_bf16 v[46:49], v[78:81], v[166:169], v[46:49]
	s_barrier
	s_add_i32 s67, 0, 0x18000
	s_add_i32 s68, 0, 0x1c000
	ds_read_b128 v[50:53], v229 offset:32768
	ds_read_b128 v[54:57], v229 offset:33792
	ds_read_b128 v[66:69], v229 offset:34816
	ds_read_b128 v[70:73], v229 offset:35840
	ds_read_b128 v[74:77], v229 offset:49152
	ds_read_b128 v[78:81], v229 offset:50176
	ds_read_b128 v[162:165], v229 offset:51200
	ds_read_b128 v[166:169], v229 offset:52224
	s_add_u32 s22, s22, 0x4000
	s_addc_u32 s23, s23, 0
	s_mov_b32 m0, s52
	ds_read_b128 v[82:85], v205 offset:32768
	ds_read_b128 v[86:89], v205 offset:33792
	ds_read_b128 v[170:173], v205 offset:34816
	ds_read_b128 v[174:177], v205 offset:35840
	ds_read_b128 v[178:181], v205 offset:36864
	ds_read_b128 v[182:185], v205 offset:37888
	ds_read_b128 v[192:195], v205 offset:38912
	ds_read_b128 v[196:199], v205 offset:39936
	global_load_lds_dwordx4 v186, s[22:23]
	s_mov_b32 m0, s53
	s_nop 0
	global_load_lds_dwordx4 v188, s[22:23]
	s_waitcnt vmcnt(8) lgkmcnt(0)
	s_barrier
	v_mfma_f32_16x16x32_bf16 v[158:161], v[50:53], v[82:85], v[158:161]
	v_mfma_f32_16x16x32_bf16 v[154:157], v[66:69], v[82:85], v[154:157]
	v_mfma_f32_16x16x32_bf16 v[142:145], v[50:53], v[170:173], v[142:145]
	v_mfma_f32_16x16x32_bf16 v[138:141], v[66:69], v[170:173], v[138:141]
	v_mfma_f32_16x16x32_bf16 v[126:129], v[50:53], v[178:181], v[126:129]
	v_mfma_f32_16x16x32_bf16 v[122:125], v[66:69], v[178:181], v[122:125]
	v_mfma_f32_16x16x32_bf16 v[110:113], v[50:53], v[192:195], v[110:113]
	v_mfma_f32_16x16x32_bf16 v[106:109], v[66:69], v[192:195], v[106:109]
	v_mfma_f32_16x16x32_bf16 v[158:161], v[54:57], v[86:89], v[158:161]
	v_mfma_f32_16x16x32_bf16 v[154:157], v[70:73], v[86:89], v[154:157]
	v_mfma_f32_16x16x32_bf16 v[142:145], v[54:57], v[174:177], v[142:145]
	v_mfma_f32_16x16x32_bf16 v[138:141], v[70:73], v[174:177], v[138:141]
	v_mfma_f32_16x16x32_bf16 v[126:129], v[54:57], v[182:185], v[126:129]
	v_mfma_f32_16x16x32_bf16 v[122:125], v[70:73], v[182:185], v[122:125]
	v_mfma_f32_16x16x32_bf16 v[110:113], v[54:57], v[196:199], v[110:113]
	v_mfma_f32_16x16x32_bf16 v[106:109], v[70:73], v[196:199], v[106:109]
	v_mfma_f32_16x16x32_bf16 v[150:153], v[74:77], v[82:85], v[150:153]
	v_mfma_f32_16x16x32_bf16 v[82:85], v[162:165], v[82:85], v[146:149]
	v_mfma_f32_16x16x32_bf16 v[146:149], v[166:169], v[86:89], v[82:85]
	v_mfma_f32_16x16x32_bf16 v[82:85], v[74:77], v[170:173], v[134:137]
	v_mfma_f32_16x16x32_bf16 v[134:137], v[78:81], v[174:177], v[82:85]
	v_mfma_f32_16x16x32_bf16 v[82:85], v[162:165], v[170:173], v[130:133]
	v_mfma_f32_16x16x32_bf16 v[130:133], v[166:169], v[174:177], v[82:85]
	v_mfma_f32_16x16x32_bf16 v[82:85], v[74:77], v[178:181], v[118:121]
	v_mfma_f32_16x16x32_bf16 v[118:121], v[78:81], v[182:185], v[82:85]
	v_mfma_f32_16x16x32_bf16 v[82:85], v[162:165], v[178:181], v[114:117]
	v_mfma_f32_16x16x32_bf16 v[114:117], v[166:169], v[182:185], v[82:85]
	v_mfma_f32_16x16x32_bf16 v[82:85], v[74:77], v[192:195], v[102:105]
	v_mfma_f32_16x16x32_bf16 v[102:105], v[78:81], v[196:199], v[82:85]
	v_mfma_f32_16x16x32_bf16 v[82:85], v[162:165], v[192:195], v[98:101]
	v_mfma_f32_16x16x32_bf16 v[150:153], v[78:81], v[86:89], v[150:153]
	v_mfma_f32_16x16x32_bf16 v[98:101], v[166:169], v[196:199], v[82:85]
	s_barrier
	s_add_u32 s22, s16, 0x8000
	s_addc_u32 s23, s17, 0
	s_add_i32 s67, s67, s49
	s_mov_b32 m0, s67
	ds_read_b128 v[82:85], v205 offset:49152
	ds_read_b128 v[170:173], v205 offset:50176
	ds_read_b128 v[174:177], v205 offset:51200
	ds_read_b128 v[178:181], v205 offset:52224
	ds_read_b128 v[182:185], v205 offset:53248
	ds_read_b128 v[192:195], v205 offset:54272
	ds_read_b128 v[196:199], v205 offset:55296
	ds_read_b128 v[212:215], v205 offset:56320
	global_load_lds_dwordx4 v186, s[22:23]
	s_add_i32 m0, s67, 0x2000
	s_add_u32 s16, s16, 0xc000
	s_addc_u32 s17, s17, 0
	global_load_lds_dwordx4 v188, s[22:23]
	s_add_i32 s22, s68, s49
	s_mov_b32 m0, s22
	s_nop 0
	global_load_lds_dwordx4 v186, s[16:17]
	s_add_i32 m0, s22, 0x2000
	s_nop 0
	global_load_lds_dwordx4 v188, s[16:17]
	s_mov_b32 m0, s60
	s_nop 0
	global_load_lds_dwordx4 v186, s[14:15]
	s_mov_b32 m0, s61
	s_nop 0
	global_load_lds_dwordx4 v188, s[14:15]
	s_waitcnt vmcnt(8) lgkmcnt(0)
	s_barrier
	v_mfma_f32_16x16x32_bf16 v[86:89], v[50:53], v[82:85], v[94:97]
	v_mfma_f32_16x16x32_bf16 v[94:97], v[54:57], v[170:173], v[86:89]
	v_mfma_f32_16x16x32_bf16 v[86:89], v[66:69], v[82:85], v[90:93]
	v_mfma_f32_16x16x32_bf16 v[62:65], v[50:53], v[174:177], v[62:65]
	v_mfma_f32_16x16x32_bf16 v[58:61], v[66:69], v[174:177], v[58:61]
	v_mfma_f32_16x16x32_bf16 v[30:33], v[50:53], v[182:185], v[30:33]
	v_mfma_f32_16x16x32_bf16 v[26:29], v[66:69], v[182:185], v[26:29]
	v_mfma_f32_16x16x32_bf16 v[14:17], v[50:53], v[196:199], v[14:17]
	v_mfma_f32_16x16x32_bf16 v[10:13], v[66:69], v[196:199], v[10:13]
	v_mfma_f32_16x16x32_bf16 v[90:93], v[70:73], v[170:173], v[86:89]
	v_mfma_f32_16x16x32_bf16 v[62:65], v[54:57], v[178:181], v[62:65]
	v_mfma_f32_16x16x32_bf16 v[58:61], v[70:73], v[178:181], v[58:61]
	v_mfma_f32_16x16x32_bf16 v[30:33], v[54:57], v[192:195], v[30:33]
	v_mfma_f32_16x16x32_bf16 v[26:29], v[70:73], v[192:195], v[26:29]
	v_mfma_f32_16x16x32_bf16 v[14:17], v[54:57], v[212:215], v[14:17]
	v_mfma_f32_16x16x32_bf16 v[10:13], v[70:73], v[212:215], v[10:13]
	v_mfma_f32_16x16x32_bf16 v[42:45], v[74:77], v[82:85], v[42:45]
	v_mfma_f32_16x16x32_bf16 v[86:89], v[78:81], v[170:173], v[42:45]
	v_mfma_f32_16x16x32_bf16 v[42:45], v[162:165], v[82:85], v[46:49]
	v_mfma_f32_16x16x32_bf16 v[38:41], v[74:77], v[174:177], v[38:41]
	v_mfma_f32_16x16x32_bf16 v[34:37], v[162:165], v[174:177], v[34:37]
	v_mfma_f32_16x16x32_bf16 v[22:25], v[74:77], v[182:185], v[22:25]
	v_mfma_f32_16x16x32_bf16 v[18:21], v[162:165], v[182:185], v[18:21]
	v_mfma_f32_16x16x32_bf16 v[6:9], v[74:77], v[196:199], v[6:9]
	v_mfma_f32_16x16x32_bf16 v[2:5], v[162:165], v[196:199], v[2:5]
	v_mfma_f32_16x16x32_bf16 v[82:85], v[166:169], v[170:173], v[42:45]
	v_mfma_f32_16x16x32_bf16 v[38:41], v[78:81], v[178:181], v[38:41]
	v_mfma_f32_16x16x32_bf16 v[34:37], v[166:169], v[178:181], v[34:37]
	v_mfma_f32_16x16x32_bf16 v[22:25], v[78:81], v[192:195], v[22:25]
	v_mfma_f32_16x16x32_bf16 v[18:21], v[166:169], v[192:195], v[18:21]
	v_mfma_f32_16x16x32_bf16 v[6:9], v[78:81], v[212:215], v[6:9]
	v_mfma_f32_16x16x32_bf16 v[2:5], v[166:169], v[212:215], v[2:5]
	s_barrier
	s_add_i32 s66, s66, 2
	s_add_u32 s12, s12, 0x10000
	s_addc_u32 s13, s13, 0
	s_add_u32 s31, s31, 0x10000
	s_addc_u32 s41, s41, 0
	s_cmp_gt_u32 s66, 29
	s_cbranch_scc0 .LBB0_1111
	s_and_b64 vcc, exec, s[24:25]
	s_cbranch_vccz .LBB0_1114
	s_barrier

.LBB0_1196:
	s_add_u32 s16, s14, 1
	s_addc_u32 s17, s15, 0
	s_lshl_b64 s[16:17], s[16:17], s60
	s_add_u32 s16, s12, s16
	s_addc_u32 s17, s13, s17
	s_cmp_eq_u32 s14, 31
	s_cselect_b32 s46, s42, s16
	s_cselect_b32 s47, s43, s17
	s_cselect_b32 s22, s44, s73
	s_cselect_b32 s23, s45, s74
	s_add_u32 s16, s46, s59
	s_addc_u32 s17, s47, 0
	s_add_i32 s75, 0, 0x10000
	s_add_i32 s78, 0, 0x14000
	ds_read_b128 v[66:69], v229
	ds_read_b128 v[70:73], v229 offset:1024
	ds_read_b128 v[74:77], v229 offset:2048
	ds_read_b128 v[78:81], v229 offset:3072
	ds_read_b128 v[164:167], v229 offset:16384
	ds_read_b128 v[168:171], v229 offset:17408
	ds_read_b128 v[172:175], v229 offset:18432
	ds_read_b128 v[176:179], v229 offset:19456
	s_lshl_b64 s[76:77], s[14:15], s60
	s_add_u32 s76, s31, s76
	s_addc_u32 s77, s41, s77
	s_add_i32 m0, s54, 0xc000
	ds_read_b128 v[180:183], v161
	ds_read_b128 v[184:187], v161 offset:1024
	ds_read_b128 v[188:191], v161 offset:2048
	ds_read_b128 v[192:195], v161 offset:3072
	ds_read_b128 v[196:199], v161 offset:4096
	ds_read_b128 v[200:203], v161 offset:5120
	ds_read_b128 v[204:207], v161 offset:6144
	ds_read_b128 v[212:215], v161 offset:7168
	global_load_lds_dwordx4 v152, s[76:77]
	s_add_i32 m0, s54, 0xe000
	s_nop 0
	global_load_lds_dwordx4 v150, s[76:77]
	s_waitcnt vmcnt(8) lgkmcnt(0)
	s_barrier
	v_mfma_f32_16x16x32_bf16 v[142:145], v[66:69], v[180:183], v[142:145]
	v_mfma_f32_16x16x32_bf16 v[138:141], v[74:77], v[180:183], v[138:141]
	v_mfma_f32_16x16x32_bf16 v[126:129], v[66:69], v[188:191], v[126:129]
	v_mfma_f32_16x16x32_bf16 v[122:125], v[74:77], v[188:191], v[122:125]
	v_mfma_f32_16x16x32_bf16 v[110:113], v[66:69], v[196:199], v[110:113]
	v_mfma_f32_16x16x32_bf16 v[106:109], v[74:77], v[196:199], v[106:109]
	v_mfma_f32_16x16x32_bf16 v[94:97], v[66:69], v[204:207], v[94:97]
	v_mfma_f32_16x16x32_bf16 v[90:93], v[74:77], v[204:207], v[90:93]
	v_mfma_f32_16x16x32_bf16 v[142:145], v[70:73], v[184:187], v[142:145]
	v_mfma_f32_16x16x32_bf16 v[138:141], v[78:81], v[184:187], v[138:141]
	v_mfma_f32_16x16x32_bf16 v[126:129], v[70:73], v[192:195], v[126:129]
	v_mfma_f32_16x16x32_bf16 v[122:125], v[78:81], v[192:195], v[122:125]
	v_mfma_f32_16x16x32_bf16 v[110:113], v[70:73], v[200:203], v[110:113]
	v_mfma_f32_16x16x32_bf16 v[106:109], v[78:81], v[200:203], v[106:109]
	v_mfma_f32_16x16x32_bf16 v[94:97], v[70:73], v[212:215], v[94:97]
	v_mfma_f32_16x16x32_bf16 v[90:93], v[78:81], v[212:215], v[90:93]
	v_mfma_f32_16x16x32_bf16 v[134:137], v[164:167], v[180:183], v[134:137]
	v_mfma_f32_16x16x32_bf16 v[130:133], v[172:175], v[180:183], v[130:133]
	v_mfma_f32_16x16x32_bf16 v[118:121], v[164:167], v[188:191], v[118:121]
	v_mfma_f32_16x16x32_bf16 v[114:117], v[172:175], v[188:191], v[114:117]
	v_mfma_f32_16x16x32_bf16 v[102:105], v[164:167], v[196:199], v[102:105]
	v_mfma_f32_16x16x32_bf16 v[98:101], v[172:175], v[196:199], v[98:101]
	v_mfma_f32_16x16x32_bf16 v[86:89], v[164:167], v[204:207], v[86:89]
	v_mfma_f32_16x16x32_bf16 v[82:85], v[172:175], v[204:207], v[82:85]
	v_mfma_f32_16x16x32_bf16 v[134:137], v[168:171], v[184:187], v[134:137]
	v_mfma_f32_16x16x32_bf16 v[130:133], v[176:179], v[184:187], v[130:133]
	v_mfma_f32_16x16x32_bf16 v[118:121], v[168:171], v[192:195], v[118:121]
	v_mfma_f32_16x16x32_bf16 v[114:117], v[176:179], v[192:195], v[114:117]
	v_mfma_f32_16x16x32_bf16 v[102:105], v[168:171], v[200:203], v[102:105]
	v_mfma_f32_16x16x32_bf16 v[98:101], v[176:179], v[200:203], v[98:101]
	v_mfma_f32_16x16x32_bf16 v[86:89], v[168:171], v[212:215], v[86:89]
	v_mfma_f32_16x16x32_bf16 v[82:85], v[176:179], v[212:215], v[82:85]
	s_barrier
	s_add_i32 s75, s75, s53
	s_mov_b32 m0, s75
	ds_read_b128 v[180:183], v161 offset:16384
	ds_read_b128 v[184:187], v161 offset:17408
	ds_read_b128 v[188:191], v161 offset:18432
	ds_read_b128 v[192:195], v161 offset:19456
	ds_read_b128 v[196:199], v161 offset:20480
	ds_read_b128 v[200:203], v161 offset:21504
	ds_read_b128 v[204:207], v161 offset:22528
	ds_read_b128 v[212:215], v161 offset:23552
	global_load_lds_dwordx4 v146, s[22:23]
	s_add_i32 m0, s75, 0x2000
	s_add_u32 s76, s22, 0x4000
	s_addc_u32 s77, s23, 0
	s_add_i32 s75, s78, s53
	global_load_lds_dwordx4 v148, s[22:23]
	s_mov_b32 m0, s75
	s_nop 0
	global_load_lds_dwordx4 v146, s[76:77]
	s_add_i32 m0, s75, 0x2000
	s_nop 0
	global_load_lds_dwordx4 v148, s[76:77]
	s_mov_b32 m0, s54
	s_nop 0
	global_load_lds_dwordx4 v152, s[46:47]
	s_mov_b32 m0, s55
	s_nop 0
	global_load_lds_dwordx4 v150, s[46:47]
	s_waitcnt vmcnt(8) lgkmcnt(0)
	s_barrier
	v_mfma_f32_16x16x32_bf16 v[62:65], v[66:69], v[180:183], v[62:65]
	v_mfma_f32_16x16x32_bf16 v[58:61], v[74:77], v[180:183], v[58:61]
	v_mfma_f32_16x16x32_bf16 v[46:49], v[66:69], v[188:191], v[46:49]
	v_mfma_f32_16x16x32_bf16 v[42:45], v[74:77], v[188:191], v[42:45]
	v_mfma_f32_16x16x32_bf16 v[30:33], v[66:69], v[196:199], v[30:33]
	v_mfma_f32_16x16x32_bf16 v[26:29], v[74:77], v[196:199], v[26:29]
	v_mfma_f32_16x16x32_bf16 v[14:17], v[66:69], v[204:207], v[14:17]
	v_mfma_f32_16x16x32_bf16 v[10:13], v[74:77], v[204:207], v[10:13]
	v_mfma_f32_16x16x32_bf16 v[62:65], v[70:73], v[184:187], v[62:65]
	v_mfma_f32_16x16x32_bf16 v[58:61], v[78:81], v[184:187], v[58:61]
	v_mfma_f32_16x16x32_bf16 v[46:49], v[70:73], v[192:195], v[46:49]
	v_mfma_f32_16x16x32_bf16 v[42:45], v[78:81], v[192:195], v[42:45]
	v_mfma_f32_16x16x32_bf16 v[30:33], v[70:73], v[200:203], v[30:33]
	v_mfma_f32_16x16x32_bf16 v[26:29], v[78:81], v[200:203], v[26:29]
	v_mfma_f32_16x16x32_bf16 v[14:17], v[70:73], v[212:215], v[14:17]
	v_mfma_f32_16x16x32_bf16 v[10:13], v[78:81], v[212:215], v[10:13]
	v_mfma_f32_16x16x32_bf16 v[54:57], v[164:167], v[180:183], v[54:57]
	v_mfma_f32_16x16x32_bf16 v[50:53], v[172:175], v[180:183], v[50:53]
	v_mfma_f32_16x16x32_bf16 v[38:41], v[164:167], v[188:191], v[38:41]
	v_mfma_f32_16x16x32_bf16 v[34:37], v[172:175], v[188:191], v[34:37]
	v_mfma_f32_16x16x32_bf16 v[22:25], v[164:167], v[196:199], v[22:25]
	v_mfma_f32_16x16x32_bf16 v[18:21], v[172:175], v[196:199], v[18:21]
	v_mfma_f32_16x16x32_bf16 v[6:9], v[164:167], v[204:207], v[6:9]
	v_mfma_f32_16x16x32_bf16 v[2:5], v[172:175], v[204:207], v[2:5]
	v_mfma_f32_16x16x32_bf16 v[54:57], v[168:171], v[184:187], v[54:57]
	v_mfma_f32_16x16x32_bf16 v[50:53], v[176:179], v[184:187], v[50:53]
	v_mfma_f32_16x16x32_bf16 v[38:41], v[168:171], v[192:195], v[38:41]
	v_mfma_f32_16x16x32_bf16 v[34:37], v[176:179], v[192:195], v[34:37]
	v_mfma_f32_16x16x32_bf16 v[22:25], v[168:171], v[200:203], v[22:25]
	v_mfma_f32_16x16x32_bf16 v[18:21], v[176:179], v[200:203], v[18:21]
	v_mfma_f32_16x16x32_bf16 v[6:9], v[168:171], v[212:215], v[6:9]
	v_mfma_f32_16x16x32_bf16 v[2:5], v[176:179], v[212:215], v[2:5]
	s_barrier
	s_add_i32 s75, 0, 0x18000
	s_add_i32 s76, 0, 0x1c000
	ds_read_b128 v[66:69], v229 offset:32768
	ds_read_b128 v[70:73], v229 offset:33792
	ds_read_b128 v[74:77], v229 offset:34816
	ds_read_b128 v[78:81], v229 offset:35840
	ds_read_b128 v[164:167], v229 offset:49152
	ds_read_b128 v[168:171], v229 offset:50176
	ds_read_b128 v[172:175], v229 offset:51200
	ds_read_b128 v[176:179], v229 offset:52224
	s_add_u32 s46, s46, s52
	s_addc_u32 s47, s47, 0
	s_mov_b32 m0, s56
	ds_read_b128 v[180:183], v161 offset:32768
	ds_read_b128 v[184:187], v161 offset:33792
	ds_read_b128 v[188:191], v161 offset:34816
	ds_read_b128 v[192:195], v161 offset:35840
	ds_read_b128 v[196:199], v161 offset:36864
	ds_read_b128 v[200:203], v161 offset:37888
	ds_read_b128 v[204:207], v161 offset:38912
	ds_read_b128 v[212:215], v161 offset:39936
	global_load_lds_dwordx4 v152, s[46:47]
	s_mov_b32 m0, s57
	s_nop 0
	global_load_lds_dwordx4 v150, s[46:47]
	s_waitcnt vmcnt(8) lgkmcnt(0)
	s_barrier
	v_mfma_f32_16x16x32_bf16 v[142:145], v[66:69], v[180:183], v[142:145]
	v_mfma_f32_16x16x32_bf16 v[138:141], v[74:77], v[180:183], v[138:141]
	v_mfma_f32_16x16x32_bf16 v[126:129], v[66:69], v[188:191], v[126:129]
	v_mfma_f32_16x16x32_bf16 v[122:125], v[74:77], v[188:191], v[122:125]
	v_mfma_f32_16x16x32_bf16 v[110:113], v[66:69], v[196:199], v[110:113]
	v_mfma_f32_16x16x32_bf16 v[106:109], v[74:77], v[196:199], v[106:109]
	v_mfma_f32_16x16x32_bf16 v[94:97], v[66:69], v[204:207], v[94:97]
	v_mfma_f32_16x16x32_bf16 v[90:93], v[74:77], v[204:207], v[90:93]
	v_mfma_f32_16x16x32_bf16 v[142:145], v[70:73], v[184:187], v[142:145]
	v_mfma_f32_16x16x32_bf16 v[138:141], v[78:81], v[184:187], v[138:141]
	v_mfma_f32_16x16x32_bf16 v[126:129], v[70:73], v[192:195], v[126:129]
	v_mfma_f32_16x16x32_bf16 v[122:125], v[78:81], v[192:195], v[122:125]
	v_mfma_f32_16x16x32_bf16 v[110:113], v[70:73], v[200:203], v[110:113]
	v_mfma_f32_16x16x32_bf16 v[106:109], v[78:81], v[200:203], v[106:109]
	v_mfma_f32_16x16x32_bf16 v[94:97], v[70:73], v[212:215], v[94:97]
	v_mfma_f32_16x16x32_bf16 v[90:93], v[78:81], v[212:215], v[90:93]
	v_mfma_f32_16x16x32_bf16 v[134:137], v[164:167], v[180:183], v[134:137]
	v_mfma_f32_16x16x32_bf16 v[130:133], v[172:175], v[180:183], v[130:133]
	v_mfma_f32_16x16x32_bf16 v[118:121], v[164:167], v[188:191], v[118:121]
	v_mfma_f32_16x16x32_bf16 v[114:117], v[172:175], v[188:191], v[114:117]
	v_mfma_f32_16x16x32_bf16 v[102:105], v[164:167], v[196:199], v[102:105]
	v_mfma_f32_16x16x32_bf16 v[98:101], v[172:175], v[196:199], v[98:101]
	v_mfma_f32_16x16x32_bf16 v[86:89], v[164:167], v[204:207], v[86:89]
	v_mfma_f32_16x16x32_bf16 v[82:85], v[172:175], v[204:207], v[82:85]
	v_mfma_f32_16x16x32_bf16 v[134:137], v[168:171], v[184:187], v[134:137]
	v_mfma_f32_16x16x32_bf16 v[130:133], v[176:179], v[184:187], v[130:133]
	v_mfma_f32_16x16x32_bf16 v[118:121], v[168:171], v[192:195], v[118:121]
	v_mfma_f32_16x16x32_bf16 v[114:117], v[176:179], v[192:195], v[114:117]
	v_mfma_f32_16x16x32_bf16 v[102:105], v[168:171], v[200:203], v[102:105]
	v_mfma_f32_16x16x32_bf16 v[98:101], v[176:179], v[200:203], v[98:101]
	v_mfma_f32_16x16x32_bf16 v[86:89], v[168:171], v[212:215], v[86:89]
	v_mfma_f32_16x16x32_bf16 v[82:85], v[176:179], v[212:215], v[82:85]
	s_barrier
	s_add_u32 s46, s22, 0x8000
	s_addc_u32 s47, s23, 0
	s_add_i32 s75, s75, s53
	s_mov_b32 m0, s75
	ds_read_b128 v[180:183], v161 offset:49152
	ds_read_b128 v[184:187], v161 offset:50176
	ds_read_b128 v[188:191], v161 offset:51200
	ds_read_b128 v[192:195], v161 offset:52224
	ds_read_b128 v[196:199], v161 offset:53248
	ds_read_b128 v[200:203], v161 offset:54272
	ds_read_b128 v[204:207], v161 offset:55296
	ds_read_b128 v[212:215], v161 offset:56320
	global_load_lds_dwordx4 v146, s[46:47]
	s_add_i32 m0, s75, 0x2000
	s_add_u32 s22, s22, 0xc000
	s_addc_u32 s23, s23, 0
	global_load_lds_dwordx4 v148, s[46:47]
	s_add_i32 s46, s76, s53
	s_mov_b32 m0, s46
	s_nop 0
	global_load_lds_dwordx4 v146, s[22:23]
	s_add_i32 m0, s46, 0x2000
	s_nop 0
	global_load_lds_dwordx4 v148, s[22:23]
	s_mov_b32 m0, s63
	s_nop 0
	global_load_lds_dwordx4 v152, s[16:17]
	s_mov_b32 m0, s64
	s_nop 0
	global_load_lds_dwordx4 v150, s[16:17]
	s_waitcnt vmcnt(8) lgkmcnt(0)
	s_barrier
	v_mfma_f32_16x16x32_bf16 v[62:65], v[66:69], v[180:183], v[62:65]
	v_mfma_f32_16x16x32_bf16 v[58:61], v[74:77], v[180:183], v[58:61]
	v_mfma_f32_16x16x32_bf16 v[46:49], v[66:69], v[188:191], v[46:49]
	v_mfma_f32_16x16x32_bf16 v[42:45], v[74:77], v[188:191], v[42:45]
	v_mfma_f32_16x16x32_bf16 v[30:33], v[66:69], v[196:199], v[30:33]
	v_mfma_f32_16x16x32_bf16 v[26:29], v[74:77], v[196:199], v[26:29]
	v_mfma_f32_16x16x32_bf16 v[14:17], v[66:69], v[204:207], v[14:17]
	v_mfma_f32_16x16x32_bf16 v[10:13], v[74:77], v[204:207], v[10:13]
	v_mfma_f32_16x16x32_bf16 v[62:65], v[70:73], v[184:187], v[62:65]
	v_mfma_f32_16x16x32_bf16 v[58:61], v[78:81], v[184:187], v[58:61]
	v_mfma_f32_16x16x32_bf16 v[46:49], v[70:73], v[192:195], v[46:49]
	v_mfma_f32_16x16x32_bf16 v[42:45], v[78:81], v[192:195], v[42:45]
	v_mfma_f32_16x16x32_bf16 v[30:33], v[70:73], v[200:203], v[30:33]
	v_mfma_f32_16x16x32_bf16 v[26:29], v[78:81], v[200:203], v[26:29]
	v_mfma_f32_16x16x32_bf16 v[14:17], v[70:73], v[212:215], v[14:17]
	v_mfma_f32_16x16x32_bf16 v[10:13], v[78:81], v[212:215], v[10:13]
	v_mfma_f32_16x16x32_bf16 v[54:57], v[164:167], v[180:183], v[54:57]
	v_mfma_f32_16x16x32_bf16 v[50:53], v[172:175], v[180:183], v[50:53]
	v_mfma_f32_16x16x32_bf16 v[38:41], v[164:167], v[188:191], v[38:41]
	v_mfma_f32_16x16x32_bf16 v[34:37], v[172:175], v[188:191], v[34:37]
	v_mfma_f32_16x16x32_bf16 v[22:25], v[164:167], v[196:199], v[22:25]
	v_mfma_f32_16x16x32_bf16 v[18:21], v[172:175], v[196:199], v[18:21]
	v_mfma_f32_16x16x32_bf16 v[6:9], v[164:167], v[204:207], v[6:9]
	v_mfma_f32_16x16x32_bf16 v[2:5], v[172:175], v[204:207], v[2:5]
	v_mfma_f32_16x16x32_bf16 v[54:57], v[168:171], v[184:187], v[54:57]
	v_mfma_f32_16x16x32_bf16 v[50:53], v[176:179], v[184:187], v[50:53]
	v_mfma_f32_16x16x32_bf16 v[38:41], v[168:171], v[192:195], v[38:41]
	v_mfma_f32_16x16x32_bf16 v[34:37], v[176:179], v[192:195], v[34:37]
	v_mfma_f32_16x16x32_bf16 v[22:25], v[168:171], v[200:203], v[22:25]
	v_mfma_f32_16x16x32_bf16 v[18:21], v[176:179], v[200:203], v[18:21]
	v_mfma_f32_16x16x32_bf16 v[6:9], v[168:171], v[212:215], v[6:9]
	v_mfma_f32_16x16x32_bf16 v[2:5], v[176:179], v[212:215], v[2:5]
	s_barrier
	s_add_u32 s14, s14, 2
	s_addc_u32 s15, s15, 0
	s_add_i32 s16, s14, -3
	s_add_u32 s73, s73, 0x10000
	s_addc_u32 s74, s74, 0
	s_cmp_gt_u32 s16, 29
	s_cbranch_scc0 .LBB0_1196
	s_and_b64 vcc, exec, s[26:27]
	s_cbranch_vccz .LBB0_1199
	s_barrier

.LBB0_1275:
	s_add_u32 s4, s2, 0x4000
	s_addc_u32 s5, s3, 0
	s_cmpk_eq_i32 s77, 0x52
	s_cselect_b32 s14, s54, s4
	s_cselect_b32 s15, s55, s5
	s_cselect_b32 s12, s56, s75
	s_cselect_b32 s13, s57, s76
	s_add_u32 s4, s14, 0x8000
	s_addc_u32 s5, s15, 0
	s_add_i32 s78, 0, 0x10000
	s_add_i32 s80, 0, 0x14000
	ds_read_b128 v[58:61], v229
	ds_read_b128 v[62:65], v229 offset:1024
	ds_read_b128 v[66:69], v229 offset:2048
	ds_read_b128 v[70:73], v229 offset:3072
	ds_read_b128 v[146:149], v229 offset:16384
	ds_read_b128 v[150:153], v229 offset:17408
	ds_read_b128 v[154:157], v229 offset:18432
	ds_read_b128 v[158:161], v229 offset:19456
	s_add_i32 m0, s59, 0xc000
	ds_read_b128 v[162:165], v225
	ds_read_b128 v[166:169], v225 offset:1024
	ds_read_b128 v[170:173], v225 offset:2048
	ds_read_b128 v[174:177], v225 offset:3072
	ds_read_b128 v[178:181], v225 offset:4096
	ds_read_b128 v[182:185], v225 offset:5120
	ds_read_b128 v[192:195], v225 offset:6144
	ds_read_b128 v[196:199], v225 offset:7168
	global_load_lds_dwordx4 v186, s[2:3]
	s_add_i32 m0, s59, 0xe000
	s_nop 0
	global_load_lds_dwordx4 v188, s[2:3]
	s_waitcnt vmcnt(8) lgkmcnt(0)
	s_barrier
	v_mfma_f32_16x16x32_bf16 v[142:145], v[58:61], v[162:165], v[142:145]
	v_mfma_f32_16x16x32_bf16 v[138:141], v[66:69], v[162:165], v[138:141]
	v_mfma_f32_16x16x32_bf16 v[126:129], v[58:61], v[170:173], v[126:129]
	v_mfma_f32_16x16x32_bf16 v[122:125], v[66:69], v[170:173], v[122:125]
	v_mfma_f32_16x16x32_bf16 v[110:113], v[58:61], v[178:181], v[110:113]
	v_mfma_f32_16x16x32_bf16 v[106:109], v[66:69], v[178:181], v[106:109]
	v_mfma_f32_16x16x32_bf16 v[94:97], v[58:61], v[192:195], v[94:97]
	v_mfma_f32_16x16x32_bf16 v[90:93], v[66:69], v[192:195], v[90:93]
	v_mfma_f32_16x16x32_bf16 v[142:145], v[62:65], v[166:169], v[142:145]
	v_mfma_f32_16x16x32_bf16 v[138:141], v[70:73], v[166:169], v[138:141]
	v_mfma_f32_16x16x32_bf16 v[126:129], v[62:65], v[174:177], v[126:129]
	v_mfma_f32_16x16x32_bf16 v[122:125], v[70:73], v[174:177], v[122:125]
	v_mfma_f32_16x16x32_bf16 v[110:113], v[62:65], v[182:185], v[110:113]
	v_mfma_f32_16x16x32_bf16 v[106:109], v[70:73], v[182:185], v[106:109]
	v_mfma_f32_16x16x32_bf16 v[94:97], v[62:65], v[196:199], v[94:97]
	v_mfma_f32_16x16x32_bf16 v[90:93], v[70:73], v[196:199], v[90:93]
	v_mfma_f32_16x16x32_bf16 v[134:137], v[146:149], v[162:165], v[134:137]
	v_mfma_f32_16x16x32_bf16 v[130:133], v[154:157], v[162:165], v[130:133]
	v_mfma_f32_16x16x32_bf16 v[118:121], v[146:149], v[170:173], v[118:121]
	v_mfma_f32_16x16x32_bf16 v[114:117], v[154:157], v[170:173], v[114:117]
	v_mfma_f32_16x16x32_bf16 v[102:105], v[146:149], v[178:181], v[102:105]
	v_mfma_f32_16x16x32_bf16 v[98:101], v[154:157], v[178:181], v[98:101]
	v_mfma_f32_16x16x32_bf16 v[86:89], v[146:149], v[192:195], v[86:89]
	v_mfma_f32_16x16x32_bf16 v[82:85], v[154:157], v[192:195], v[82:85]
	v_mfma_f32_16x16x32_bf16 v[134:137], v[150:153], v[166:169], v[134:137]
	v_mfma_f32_16x16x32_bf16 v[130:133], v[158:161], v[166:169], v[130:133]
	v_mfma_f32_16x16x32_bf16 v[118:121], v[150:153], v[174:177], v[118:121]
	v_mfma_f32_16x16x32_bf16 v[114:117], v[158:161], v[174:177], v[114:117]
	v_mfma_f32_16x16x32_bf16 v[102:105], v[150:153], v[182:185], v[102:105]
	v_mfma_f32_16x16x32_bf16 v[98:101], v[158:161], v[182:185], v[98:101]
	v_mfma_f32_16x16x32_bf16 v[86:89], v[150:153], v[196:199], v[86:89]
	v_mfma_f32_16x16x32_bf16 v[82:85], v[158:161], v[196:199], v[82:85]
	s_barrier
	s_add_i32 s78, s78, s58
	s_mov_b32 m0, s78
	ds_read_b128 v[162:165], v225 offset:16384
	ds_read_b128 v[166:169], v225 offset:17408
	ds_read_b128 v[170:173], v225 offset:18432
	ds_read_b128 v[174:177], v225 offset:19456
	ds_read_b128 v[178:181], v225 offset:20480
	ds_read_b128 v[182:185], v225 offset:21504
	ds_read_b128 v[192:195], v225 offset:22528
	ds_read_b128 v[196:199], v225 offset:23552
	global_load_lds_dwordx4 v186, s[12:13]
	s_add_i32 m0, s78, 0x2000
	s_add_u32 s78, s12, 0x4000
	s_addc_u32 s79, s13, 0
	s_add_i32 s80, s80, s58
	global_load_lds_dwordx4 v188, s[12:13]
	s_mov_b32 m0, s80
	s_nop 0
	global_load_lds_dwordx4 v186, s[78:79]
	s_add_i32 m0, s80, 0x2000
	s_nop 0
	global_load_lds_dwordx4 v188, s[78:79]
	s_mov_b32 m0, s59
	s_nop 0
	global_load_lds_dwordx4 v186, s[14:15]
	s_mov_b32 m0, s60
	s_nop 0
	global_load_lds_dwordx4 v188, s[14:15]
	s_waitcnt vmcnt(8) lgkmcnt(0)
	s_barrier
	v_mfma_f32_16x16x32_bf16 v[78:81], v[58:61], v[162:165], v[78:81]
	v_mfma_f32_16x16x32_bf16 v[74:77], v[66:69], v[162:165], v[74:77]
	v_mfma_f32_16x16x32_bf16 v[46:49], v[58:61], v[170:173], v[46:49]
	v_mfma_f32_16x16x32_bf16 v[42:45], v[66:69], v[170:173], v[42:45]
	v_mfma_f32_16x16x32_bf16 v[30:33], v[58:61], v[178:181], v[30:33]
	v_mfma_f32_16x16x32_bf16 v[26:29], v[66:69], v[178:181], v[26:29]
	v_mfma_f32_16x16x32_bf16 v[14:17], v[58:61], v[192:195], v[14:17]
	v_mfma_f32_16x16x32_bf16 v[10:13], v[66:69], v[192:195], v[10:13]
	v_mfma_f32_16x16x32_bf16 v[78:81], v[62:65], v[166:169], v[78:81]
	v_mfma_f32_16x16x32_bf16 v[74:77], v[70:73], v[166:169], v[74:77]
	v_mfma_f32_16x16x32_bf16 v[46:49], v[62:65], v[174:177], v[46:49]
	v_mfma_f32_16x16x32_bf16 v[42:45], v[70:73], v[174:177], v[42:45]
	v_mfma_f32_16x16x32_bf16 v[30:33], v[62:65], v[182:185], v[30:33]
	v_mfma_f32_16x16x32_bf16 v[26:29], v[70:73], v[182:185], v[26:29]
	v_mfma_f32_16x16x32_bf16 v[14:17], v[62:65], v[196:199], v[14:17]
	v_mfma_f32_16x16x32_bf16 v[10:13], v[70:73], v[196:199], v[10:13]
	v_mfma_f32_16x16x32_bf16 v[54:57], v[146:149], v[162:165], v[54:57]
	v_mfma_f32_16x16x32_bf16 v[50:53], v[154:157], v[162:165], v[50:53]
	v_mfma_f32_16x16x32_bf16 v[38:41], v[146:149], v[170:173], v[38:41]
	v_mfma_f32_16x16x32_bf16 v[34:37], v[154:157], v[170:173], v[34:37]
	v_mfma_f32_16x16x32_bf16 v[22:25], v[146:149], v[178:181], v[22:25]
	v_mfma_f32_16x16x32_bf16 v[18:21], v[154:157], v[178:181], v[18:21]
	v_mfma_f32_16x16x32_bf16 v[6:9], v[146:149], v[192:195], v[6:9]
	v_mfma_f32_16x16x32_bf16 v[2:5], v[154:157], v[192:195], v[2:5]
	v_mfma_f32_16x16x32_bf16 v[54:57], v[150:153], v[166:169], v[54:57]
	v_mfma_f32_16x16x32_bf16 v[50:53], v[158:161], v[166:169], v[50:53]
	v_mfma_f32_16x16x32_bf16 v[38:41], v[150:153], v[174:177], v[38:41]
	v_mfma_f32_16x16x32_bf16 v[34:37], v[158:161], v[174:177], v[34:37]
	v_mfma_f32_16x16x32_bf16 v[22:25], v[150:153], v[182:185], v[22:25]
	v_mfma_f32_16x16x32_bf16 v[18:21], v[158:161], v[182:185], v[18:21]
	v_mfma_f32_16x16x32_bf16 v[6:9], v[150:153], v[196:199], v[6:9]
	v_mfma_f32_16x16x32_bf16 v[2:5], v[158:161], v[196:199], v[2:5]
	s_barrier
	s_add_i32 s78, 0, 0x18000
	s_add_i32 s79, 0, 0x1c000
	ds_read_b128 v[58:61], v229 offset:32768
	ds_read_b128 v[62:65], v229 offset:33792
	ds_read_b128 v[66:69], v229 offset:34816
	ds_read_b128 v[70:73], v229 offset:35840
	ds_read_b128 v[146:149], v229 offset:49152
	ds_read_b128 v[150:153], v229 offset:50176
	ds_read_b128 v[154:157], v229 offset:51200
	ds_read_b128 v[158:161], v229 offset:52224
	s_add_u32 s14, s14, 0x4000
	s_addc_u32 s15, s15, 0
	s_mov_b32 m0, s61
	ds_read_b128 v[162:165], v225 offset:32768
	ds_read_b128 v[166:169], v225 offset:33792
	ds_read_b128 v[170:173], v225 offset:34816
	ds_read_b128 v[174:177], v225 offset:35840
	ds_read_b128 v[178:181], v225 offset:36864
	ds_read_b128 v[182:185], v225 offset:37888
	ds_read_b128 v[192:195], v225 offset:38912
	ds_read_b128 v[196:199], v225 offset:39936
	global_load_lds_dwordx4 v186, s[14:15]
	s_mov_b32 m0, s62
	s_nop 0
	global_load_lds_dwordx4 v188, s[14:15]
	s_waitcnt vmcnt(8) lgkmcnt(0)
	s_barrier
	v_mfma_f32_16x16x32_bf16 v[142:145], v[58:61], v[162:165], v[142:145]
	v_mfma_f32_16x16x32_bf16 v[138:141], v[66:69], v[162:165], v[138:141]
	v_mfma_f32_16x16x32_bf16 v[126:129], v[58:61], v[170:173], v[126:129]
	v_mfma_f32_16x16x32_bf16 v[122:125], v[66:69], v[170:173], v[122:125]
	v_mfma_f32_16x16x32_bf16 v[110:113], v[58:61], v[178:181], v[110:113]
	v_mfma_f32_16x16x32_bf16 v[106:109], v[66:69], v[178:181], v[106:109]
	v_mfma_f32_16x16x32_bf16 v[94:97], v[58:61], v[192:195], v[94:97]
	v_mfma_f32_16x16x32_bf16 v[90:93], v[66:69], v[192:195], v[90:93]
	v_mfma_f32_16x16x32_bf16 v[142:145], v[62:65], v[166:169], v[142:145]
	v_mfma_f32_16x16x32_bf16 v[138:141], v[70:73], v[166:169], v[138:141]
	v_mfma_f32_16x16x32_bf16 v[126:129], v[62:65], v[174:177], v[126:129]
	v_mfma_f32_16x16x32_bf16 v[122:125], v[70:73], v[174:177], v[122:125]
	v_mfma_f32_16x16x32_bf16 v[110:113], v[62:65], v[182:185], v[110:113]
	v_mfma_f32_16x16x32_bf16 v[106:109], v[70:73], v[182:185], v[106:109]
	v_mfma_f32_16x16x32_bf16 v[94:97], v[62:65], v[196:199], v[94:97]
	v_mfma_f32_16x16x32_bf16 v[90:93], v[70:73], v[196:199], v[90:93]
	v_mfma_f32_16x16x32_bf16 v[134:137], v[146:149], v[162:165], v[134:137]
	v_mfma_f32_16x16x32_bf16 v[130:133], v[154:157], v[162:165], v[130:133]
	v_mfma_f32_16x16x32_bf16 v[118:121], v[146:149], v[170:173], v[118:121]
	v_mfma_f32_16x16x32_bf16 v[114:117], v[154:157], v[170:173], v[114:117]
	v_mfma_f32_16x16x32_bf16 v[102:105], v[146:149], v[178:181], v[102:105]
	v_mfma_f32_16x16x32_bf16 v[98:101], v[154:157], v[178:181], v[98:101]
	v_mfma_f32_16x16x32_bf16 v[86:89], v[146:149], v[192:195], v[86:89]
	v_mfma_f32_16x16x32_bf16 v[82:85], v[154:157], v[192:195], v[82:85]
	v_mfma_f32_16x16x32_bf16 v[134:137], v[150:153], v[166:169], v[134:137]
	v_mfma_f32_16x16x32_bf16 v[130:133], v[158:161], v[166:169], v[130:133]
	v_mfma_f32_16x16x32_bf16 v[118:121], v[150:153], v[174:177], v[118:121]
	v_mfma_f32_16x16x32_bf16 v[114:117], v[158:161], v[174:177], v[114:117]
	v_mfma_f32_16x16x32_bf16 v[102:105], v[150:153], v[182:185], v[102:105]
	v_mfma_f32_16x16x32_bf16 v[98:101], v[158:161], v[182:185], v[98:101]
	v_mfma_f32_16x16x32_bf16 v[86:89], v[150:153], v[196:199], v[86:89]
	v_mfma_f32_16x16x32_bf16 v[82:85], v[158:161], v[196:199], v[82:85]
	s_barrier
	s_add_u32 s14, s12, 0x8000
	s_addc_u32 s15, s13, 0
	s_add_i32 s78, s78, s58
	s_mov_b32 m0, s78
	ds_read_b128 v[162:165], v225 offset:49152
	ds_read_b128 v[166:169], v225 offset:50176
	ds_read_b128 v[170:173], v225 offset:51200
	ds_read_b128 v[174:177], v225 offset:52224
	ds_read_b128 v[178:181], v225 offset:53248
	ds_read_b128 v[182:185], v225 offset:54272
	ds_read_b128 v[192:195], v225 offset:55296
	ds_read_b128 v[196:199], v225 offset:56320
	global_load_lds_dwordx4 v186, s[14:15]
	s_add_i32 m0, s78, 0x2000
	s_add_u32 s12, s12, 0xc000
	s_addc_u32 s13, s13, 0
	global_load_lds_dwordx4 v188, s[14:15]
	s_add_i32 s14, s79, s58
	s_mov_b32 m0, s14
	s_nop 0
	global_load_lds_dwordx4 v186, s[12:13]
	s_add_i32 m0, s14, 0x2000
	s_nop 0
	global_load_lds_dwordx4 v188, s[12:13]
	s_mov_b32 m0, s65
	s_nop 0
	global_load_lds_dwordx4 v186, s[4:5]
	s_mov_b32 m0, s66
	s_nop 0
	global_load_lds_dwordx4 v188, s[4:5]
	s_waitcnt vmcnt(8) lgkmcnt(0)
	s_barrier
	v_mfma_f32_16x16x32_bf16 v[78:81], v[58:61], v[162:165], v[78:81]
	v_mfma_f32_16x16x32_bf16 v[74:77], v[66:69], v[162:165], v[74:77]
	v_mfma_f32_16x16x32_bf16 v[46:49], v[58:61], v[170:173], v[46:49]
	v_mfma_f32_16x16x32_bf16 v[42:45], v[66:69], v[170:173], v[42:45]
	v_mfma_f32_16x16x32_bf16 v[30:33], v[58:61], v[178:181], v[30:33]
	v_mfma_f32_16x16x32_bf16 v[26:29], v[66:69], v[178:181], v[26:29]
	v_mfma_f32_16x16x32_bf16 v[14:17], v[58:61], v[192:195], v[14:17]
	v_mfma_f32_16x16x32_bf16 v[10:13], v[66:69], v[192:195], v[10:13]
	v_mfma_f32_16x16x32_bf16 v[78:81], v[62:65], v[166:169], v[78:81]
	v_mfma_f32_16x16x32_bf16 v[74:77], v[70:73], v[166:169], v[74:77]
	v_mfma_f32_16x16x32_bf16 v[46:49], v[62:65], v[174:177], v[46:49]
	v_mfma_f32_16x16x32_bf16 v[42:45], v[70:73], v[174:177], v[42:45]
	v_mfma_f32_16x16x32_bf16 v[30:33], v[62:65], v[182:185], v[30:33]
	v_mfma_f32_16x16x32_bf16 v[26:29], v[70:73], v[182:185], v[26:29]
	v_mfma_f32_16x16x32_bf16 v[14:17], v[62:65], v[196:199], v[14:17]
	v_mfma_f32_16x16x32_bf16 v[10:13], v[70:73], v[196:199], v[10:13]
	v_mfma_f32_16x16x32_bf16 v[54:57], v[146:149], v[162:165], v[54:57]
	v_mfma_f32_16x16x32_bf16 v[50:53], v[154:157], v[162:165], v[50:53]
	v_mfma_f32_16x16x32_bf16 v[38:41], v[146:149], v[170:173], v[38:41]
	v_mfma_f32_16x16x32_bf16 v[34:37], v[154:157], v[170:173], v[34:37]
	v_mfma_f32_16x16x32_bf16 v[22:25], v[146:149], v[178:181], v[22:25]
	v_mfma_f32_16x16x32_bf16 v[18:21], v[154:157], v[178:181], v[18:21]
	v_mfma_f32_16x16x32_bf16 v[6:9], v[146:149], v[192:195], v[6:9]
	v_mfma_f32_16x16x32_bf16 v[2:5], v[154:157], v[192:195], v[2:5]
	v_mfma_f32_16x16x32_bf16 v[54:57], v[150:153], v[166:169], v[54:57]
	v_mfma_f32_16x16x32_bf16 v[50:53], v[158:161], v[166:169], v[50:53]
	v_mfma_f32_16x16x32_bf16 v[38:41], v[150:153], v[174:177], v[38:41]
	v_mfma_f32_16x16x32_bf16 v[34:37], v[158:161], v[174:177], v[34:37]
	v_mfma_f32_16x16x32_bf16 v[22:25], v[150:153], v[182:185], v[22:25]
	v_mfma_f32_16x16x32_bf16 v[18:21], v[158:161], v[182:185], v[18:21]
	v_mfma_f32_16x16x32_bf16 v[6:9], v[150:153], v[196:199], v[6:9]
	v_mfma_f32_16x16x32_bf16 v[2:5], v[158:161], v[196:199], v[2:5]
	s_barrier
	s_add_i32 s77, s77, 2
	s_add_u32 s2, s2, 0x10000
	s_addc_u32 s3, s3, 0
	s_add_u32 s75, s75, 0x10000
	s_addc_u32 s76, s76, 0
	s_cmpk_gt_u32 s77, 0x53
	s_cbranch_scc0 .LBB0_1275
	s_and_b64 vcc, exec, s[48:49]
	s_cbranch_vccz .LBB0_1278
	s_barrier
